# v ring tail trim: leave the v sweep after the last real batch instead of running the last turn's four padding batches
# speedup vs baseline: 1.0062x; 1.0062x over previous
.LV_t0_s1:
	s_cmp_eq_u32 s21, 255
	s_cbranch_scc1 .LV_done
	s_waitcnt lgkmcnt(0)
	buffer_load_dwordx4 v[128:131], v[232:233], s[60:63], 0 idxen offen
	buffer_load_dwordx4 v[132:135], v[234:235], s[60:63], 0 idxen offen
	buffer_load_dwordx4 v[136:139], v[236:237], s[60:63], 0 idxen offen
	buffer_load_dwordx4 v[140:143], v[238:239], s[60:63], 0 idxen offen
	ds_read_b32 v232, v213 offset:96
	ds_read_b32 v234, v213 offset:100
	ds_read_b32 v236, v213 offset:104
	ds_read_b32 v238, v213 offset:108
	ds_read_b128 v[248:251], v213 offset:5024
	s_waitcnt vmcnt(16)
	v_cvt_pk_f32_fp8_e32 v[224:225], v144
	v_cvt_pk_f32_fp8_sdwa v[226:227], v144 src0_sel:WORD_1
	v_cvt_pk_f32_fp8_e32 v[228:229], v145
	v_cvt_pk_f32_fp8_sdwa v[230:231], v145 src0_sel:WORD_1
	v_pk_fma_f32 v[0:1], v[224:225], v[252:253], v[0:1] op_sel_hi:[1,0,1]
	v_pk_fma_f32 v[2:3], v[226:227], v[252:253], v[2:3] op_sel_hi:[1,0,1]
	v_pk_fma_f32 v[4:5], v[228:229], v[252:253], v[4:5] op_sel_hi:[1,0,1]
	v_pk_fma_f32 v[6:7], v[230:231], v[252:253], v[6:7] op_sel_hi:[1,0,1]
	v_cvt_pk_f32_fp8_e32 v[224:225], v146
	v_cvt_pk_f32_fp8_sdwa v[226:227], v146 src0_sel:WORD_1
	v_cvt_pk_f32_fp8_e32 v[228:229], v147
	v_cvt_pk_f32_fp8_sdwa v[230:231], v147 src0_sel:WORD_1
	v_pk_fma_f32 v[8:9], v[224:225], v[252:253], v[8:9] op_sel_hi:[1,0,1]
	v_pk_fma_f32 v[10:11], v[226:227], v[252:253], v[10:11] op_sel_hi:[1,0,1]
	v_pk_fma_f32 v[12:13], v[228:229], v[252:253], v[12:13] op_sel_hi:[1,0,1]
	v_pk_fma_f32 v[14:15], v[230:231], v[252:253], v[14:15] op_sel_hi:[1,0,1]
	v_cvt_pk_f32_fp8_e32 v[224:225], v148
	v_cvt_pk_f32_fp8_sdwa v[226:227], v148 src0_sel:WORD_1
	v_cvt_pk_f32_fp8_e32 v[228:229], v149
	v_cvt_pk_f32_fp8_sdwa v[230:231], v149 src0_sel:WORD_1
	v_pk_fma_f32 v[0:1], v[224:225], v[252:253], v[0:1] op_sel:[0,1,0] op_sel_hi:[1,1,1]
	v_pk_fma_f32 v[2:3], v[226:227], v[252:253], v[2:3] op_sel:[0,1,0] op_sel_hi:[1,1,1]
	v_pk_fma_f32 v[4:5], v[228:229], v[252:253], v[4:5] op_sel:[0,1,0] op_sel_hi:[1,1,1]
	v_pk_fma_f32 v[6:7], v[230:231], v[252:253], v[6:7] op_sel:[0,1,0] op_sel_hi:[1,1,1]
	v_cvt_pk_f32_fp8_e32 v[224:225], v150
	v_cvt_pk_f32_fp8_sdwa v[226:227], v150 src0_sel:WORD_1
	v_cvt_pk_f32_fp8_e32 v[228:229], v151
	v_cvt_pk_f32_fp8_sdwa v[230:231], v151 src0_sel:WORD_1
	v_pk_fma_f32 v[8:9], v[224:225], v[252:253], v[8:9] op_sel:[0,1,0] op_sel_hi:[1,1,1]
	v_pk_fma_f32 v[10:11], v[226:227], v[252:253], v[10:11] op_sel:[0,1,0] op_sel_hi:[1,1,1]
	v_pk_fma_f32 v[12:13], v[228:229], v[252:253], v[12:13] op_sel:[0,1,0] op_sel_hi:[1,1,1]
	v_pk_fma_f32 v[14:15], v[230:231], v[252:253], v[14:15] op_sel:[0,1,0] op_sel_hi:[1,1,1]
	v_cvt_pk_f32_fp8_e32 v[224:225], v152
	v_cvt_pk_f32_fp8_sdwa v[226:227], v152 src0_sel:WORD_1
	v_cvt_pk_f32_fp8_e32 v[228:229], v153
	v_cvt_pk_f32_fp8_sdwa v[230:231], v153 src0_sel:WORD_1
	v_pk_fma_f32 v[0:1], v[224:225], v[254:255], v[0:1] op_sel_hi:[1,0,1]
	v_pk_fma_f32 v[2:3], v[226:227], v[254:255], v[2:3] op_sel_hi:[1,0,1]
	v_pk_fma_f32 v[4:5], v[228:229], v[254:255], v[4:5] op_sel_hi:[1,0,1]
	v_pk_fma_f32 v[6:7], v[230:231], v[254:255], v[6:7] op_sel_hi:[1,0,1]
	v_cvt_pk_f32_fp8_e32 v[224:225], v154
	v_cvt_pk_f32_fp8_sdwa v[226:227], v154 src0_sel:WORD_1
	v_cvt_pk_f32_fp8_e32 v[228:229], v155
	v_cvt_pk_f32_fp8_sdwa v[230:231], v155 src0_sel:WORD_1
	v_pk_fma_f32 v[8:9], v[224:225], v[254:255], v[8:9] op_sel_hi:[1,0,1]
	v_pk_fma_f32 v[10:11], v[226:227], v[254:255], v[10:11] op_sel_hi:[1,0,1]
	v_pk_fma_f32 v[12:13], v[228:229], v[254:255], v[12:13] op_sel_hi:[1,0,1]
	v_pk_fma_f32 v[14:15], v[230:231], v[254:255], v[14:15] op_sel_hi:[1,0,1]
	v_cvt_pk_f32_fp8_e32 v[224:225], v156
	v_cvt_pk_f32_fp8_sdwa v[226:227], v156 src0_sel:WORD_1
	v_cvt_pk_f32_fp8_e32 v[228:229], v157
	v_cvt_pk_f32_fp8_sdwa v[230:231], v157 src0_sel:WORD_1
	v_pk_fma_f32 v[0:1], v[224:225], v[254:255], v[0:1] op_sel:[0,1,0] op_sel_hi:[1,1,1]
	v_pk_fma_f32 v[2:3], v[226:227], v[254:255], v[2:3] op_sel:[0,1,0] op_sel_hi:[1,1,1]
	v_pk_fma_f32 v[4:5], v[228:229], v[254:255], v[4:5] op_sel:[0,1,0] op_sel_hi:[1,1,1]
	v_pk_fma_f32 v[6:7], v[230:231], v[254:255], v[6:7] op_sel:[0,1,0] op_sel_hi:[1,1,1]
	v_cvt_pk_f32_fp8_e32 v[224:225], v158
	v_cvt_pk_f32_fp8_sdwa v[226:227], v158 src0_sel:WORD_1
	v_cvt_pk_f32_fp8_e32 v[228:229], v159
	v_cvt_pk_f32_fp8_sdwa v[230:231], v159 src0_sel:WORD_1
	v_pk_fma_f32 v[8:9], v[224:225], v[254:255], v[8:9] op_sel:[0,1,0] op_sel_hi:[1,1,1]
	v_pk_fma_f32 v[10:11], v[226:227], v[254:255], v[10:11] op_sel:[0,1,0] op_sel_hi:[1,1,1]
	v_pk_fma_f32 v[12:13], v[228:229], v[254:255], v[12:13] op_sel:[0,1,0] op_sel_hi:[1,1,1]
	v_pk_fma_f32 v[14:15], v[230:231], v[254:255], v[14:15] op_sel:[0,1,0] op_sel_hi:[1,1,1]
	s_sub_i32 s90, s90, 1
	s_cmp_eq_u32 s90, 0
	s_cbranch_scc1 .LV_sw2

.LV_t1_s1:
	s_cmp_eq_u32 s21, 255
	s_cbranch_scc1 .LV_done
	s_waitcnt lgkmcnt(0)
	buffer_load_dwordx4 v[128:131], v[232:233], s[60:63], 0 idxen offen
	buffer_load_dwordx4 v[132:135], v[234:235], s[60:63], 0 idxen offen
	buffer_load_dwordx4 v[136:139], v[236:237], s[60:63], 0 idxen offen
	buffer_load_dwordx4 v[140:143], v[238:239], s[60:63], 0 idxen offen
	ds_read_b32 v232, v213 offset:96
	ds_read_b32 v234, v213 offset:100
	ds_read_b32 v236, v213 offset:104
	ds_read_b32 v238, v213 offset:108
	ds_read_b128 v[248:251], v213 offset:5024
	s_waitcnt vmcnt(16)
	v_cvt_pk_f32_fp8_e32 v[224:225], v144
	v_cvt_pk_f32_fp8_sdwa v[226:227], v144 src0_sel:WORD_1
	v_cvt_pk_f32_fp8_e32 v[228:229], v145
	v_cvt_pk_f32_fp8_sdwa v[230:231], v145 src0_sel:WORD_1
	v_pk_fma_f32 v[16:17], v[224:225], v[252:253], v[16:17] op_sel_hi:[1,0,1]
	v_pk_fma_f32 v[18:19], v[226:227], v[252:253], v[18:19] op_sel_hi:[1,0,1]
	v_pk_fma_f32 v[20:21], v[228:229], v[252:253], v[20:21] op_sel_hi:[1,0,1]
	v_pk_fma_f32 v[22:23], v[230:231], v[252:253], v[22:23] op_sel_hi:[1,0,1]
	v_cvt_pk_f32_fp8_e32 v[224:225], v146
	v_cvt_pk_f32_fp8_sdwa v[226:227], v146 src0_sel:WORD_1
	v_cvt_pk_f32_fp8_e32 v[228:229], v147
	v_cvt_pk_f32_fp8_sdwa v[230:231], v147 src0_sel:WORD_1
	v_pk_fma_f32 v[24:25], v[224:225], v[252:253], v[24:25] op_sel_hi:[1,0,1]
	v_pk_fma_f32 v[26:27], v[226:227], v[252:253], v[26:27] op_sel_hi:[1,0,1]
	v_pk_fma_f32 v[28:29], v[228:229], v[252:253], v[28:29] op_sel_hi:[1,0,1]
	v_pk_fma_f32 v[30:31], v[230:231], v[252:253], v[30:31] op_sel_hi:[1,0,1]
	v_cvt_pk_f32_fp8_e32 v[224:225], v148
	v_cvt_pk_f32_fp8_sdwa v[226:227], v148 src0_sel:WORD_1
	v_cvt_pk_f32_fp8_e32 v[228:229], v149
	v_cvt_pk_f32_fp8_sdwa v[230:231], v149 src0_sel:WORD_1
	v_pk_fma_f32 v[16:17], v[224:225], v[252:253], v[16:17] op_sel:[0,1,0] op_sel_hi:[1,1,1]
	v_pk_fma_f32 v[18:19], v[226:227], v[252:253], v[18:19] op_sel:[0,1,0] op_sel_hi:[1,1,1]
	v_pk_fma_f32 v[20:21], v[228:229], v[252:253], v[20:21] op_sel:[0,1,0] op_sel_hi:[1,1,1]
	v_pk_fma_f32 v[22:23], v[230:231], v[252:253], v[22:23] op_sel:[0,1,0] op_sel_hi:[1,1,1]
	v_cvt_pk_f32_fp8_e32 v[224:225], v150
	v_cvt_pk_f32_fp8_sdwa v[226:227], v150 src0_sel:WORD_1
	v_cvt_pk_f32_fp8_e32 v[228:229], v151
	v_cvt_pk_f32_fp8_sdwa v[230:231], v151 src0_sel:WORD_1
	v_pk_fma_f32 v[24:25], v[224:225], v[252:253], v[24:25] op_sel:[0,1,0] op_sel_hi:[1,1,1]
	v_pk_fma_f32 v[26:27], v[226:227], v[252:253], v[26:27] op_sel:[0,1,0] op_sel_hi:[1,1,1]
	v_pk_fma_f32 v[28:29], v[228:229], v[252:253], v[28:29] op_sel:[0,1,0] op_sel_hi:[1,1,1]
	v_pk_fma_f32 v[30:31], v[230:231], v[252:253], v[30:31] op_sel:[0,1,0] op_sel_hi:[1,1,1]
	v_cvt_pk_f32_fp8_e32 v[224:225], v152
	v_cvt_pk_f32_fp8_sdwa v[226:227], v152 src0_sel:WORD_1
	v_cvt_pk_f32_fp8_e32 v[228:229], v153
	v_cvt_pk_f32_fp8_sdwa v[230:231], v153 src0_sel:WORD_1
	v_pk_fma_f32 v[16:17], v[224:225], v[254:255], v[16:17] op_sel_hi:[1,0,1]
	v_pk_fma_f32 v[18:19], v[226:227], v[254:255], v[18:19] op_sel_hi:[1,0,1]
	v_pk_fma_f32 v[20:21], v[228:229], v[254:255], v[20:21] op_sel_hi:[1,0,1]
	v_pk_fma_f32 v[22:23], v[230:231], v[254:255], v[22:23] op_sel_hi:[1,0,1]
	v_cvt_pk_f32_fp8_e32 v[224:225], v154
	v_cvt_pk_f32_fp8_sdwa v[226:227], v154 src0_sel:WORD_1
	v_cvt_pk_f32_fp8_e32 v[228:229], v155
	v_cvt_pk_f32_fp8_sdwa v[230:231], v155 src0_sel:WORD_1
	v_pk_fma_f32 v[24:25], v[224:225], v[254:255], v[24:25] op_sel_hi:[1,0,1]
	v_pk_fma_f32 v[26:27], v[226:227], v[254:255], v[26:27] op_sel_hi:[1,0,1]
	v_pk_fma_f32 v[28:29], v[228:229], v[254:255], v[28:29] op_sel_hi:[1,0,1]
	v_pk_fma_f32 v[30:31], v[230:231], v[254:255], v[30:31] op_sel_hi:[1,0,1]
	v_cvt_pk_f32_fp8_e32 v[224:225], v156
	v_cvt_pk_f32_fp8_sdwa v[226:227], v156 src0_sel:WORD_1
	v_cvt_pk_f32_fp8_e32 v[228:229], v157
	v_cvt_pk_f32_fp8_sdwa v[230:231], v157 src0_sel:WORD_1
	v_pk_fma_f32 v[16:17], v[224:225], v[254:255], v[16:17] op_sel:[0,1,0] op_sel_hi:[1,1,1]
	v_pk_fma_f32 v[18:19], v[226:227], v[254:255], v[18:19] op_sel:[0,1,0] op_sel_hi:[1,1,1]
	v_pk_fma_f32 v[20:21], v[228:229], v[254:255], v[20:21] op_sel:[0,1,0] op_sel_hi:[1,1,1]
	v_pk_fma_f32 v[22:23], v[230:231], v[254:255], v[22:23] op_sel:[0,1,0] op_sel_hi:[1,1,1]
	v_cvt_pk_f32_fp8_e32 v[224:225], v158
	v_cvt_pk_f32_fp8_sdwa v[226:227], v158 src0_sel:WORD_1
	v_cvt_pk_f32_fp8_e32 v[228:229], v159
	v_cvt_pk_f32_fp8_sdwa v[230:231], v159 src0_sel:WORD_1
	v_pk_fma_f32 v[24:25], v[224:225], v[254:255], v[24:25] op_sel:[0,1,0] op_sel_hi:[1,1,1]
	v_pk_fma_f32 v[26:27], v[226:227], v[254:255], v[26:27] op_sel:[0,1,0] op_sel_hi:[1,1,1]
	v_pk_fma_f32 v[28:29], v[228:229], v[254:255], v[28:29] op_sel:[0,1,0] op_sel_hi:[1,1,1]
	v_pk_fma_f32 v[30:31], v[230:231], v[254:255], v[30:31] op_sel:[0,1,0] op_sel_hi:[1,1,1]
	s_sub_i32 s90, s90, 1
	s_cmp_eq_u32 s90, 0
	s_cbranch_scc1 .LV_sw2

.LV_t2_s1:
	s_cmp_eq_u32 s21, 255
	s_cbranch_scc1 .LV_done
	s_waitcnt lgkmcnt(0)
	buffer_load_dwordx4 v[128:131], v[232:233], s[60:63], 0 idxen offen
	buffer_load_dwordx4 v[132:135], v[234:235], s[60:63], 0 idxen offen
	buffer_load_dwordx4 v[136:139], v[236:237], s[60:63], 0 idxen offen
	buffer_load_dwordx4 v[140:143], v[238:239], s[60:63], 0 idxen offen
	ds_read_b32 v232, v213 offset:96
	ds_read_b32 v234, v213 offset:100
	ds_read_b32 v236, v213 offset:104
	ds_read_b32 v238, v213 offset:108
	ds_read_b128 v[248:251], v213 offset:5024
	s_waitcnt vmcnt(16)
	v_cvt_pk_f32_fp8_e32 v[224:225], v144
	v_cvt_pk_f32_fp8_sdwa v[226:227], v144 src0_sel:WORD_1
	v_cvt_pk_f32_fp8_e32 v[228:229], v145
	v_cvt_pk_f32_fp8_sdwa v[230:231], v145 src0_sel:WORD_1
	v_pk_fma_f32 v[32:33], v[224:225], v[252:253], v[32:33] op_sel_hi:[1,0,1]
	v_pk_fma_f32 v[34:35], v[226:227], v[252:253], v[34:35] op_sel_hi:[1,0,1]
	v_pk_fma_f32 v[36:37], v[228:229], v[252:253], v[36:37] op_sel_hi:[1,0,1]
	v_pk_fma_f32 v[38:39], v[230:231], v[252:253], v[38:39] op_sel_hi:[1,0,1]
	v_cvt_pk_f32_fp8_e32 v[224:225], v146
	v_cvt_pk_f32_fp8_sdwa v[226:227], v146 src0_sel:WORD_1
	v_cvt_pk_f32_fp8_e32 v[228:229], v147
	v_cvt_pk_f32_fp8_sdwa v[230:231], v147 src0_sel:WORD_1
	v_pk_fma_f32 v[40:41], v[224:225], v[252:253], v[40:41] op_sel_hi:[1,0,1]
	v_pk_fma_f32 v[42:43], v[226:227], v[252:253], v[42:43] op_sel_hi:[1,0,1]
	v_pk_fma_f32 v[44:45], v[228:229], v[252:253], v[44:45] op_sel_hi:[1,0,1]
	v_pk_fma_f32 v[46:47], v[230:231], v[252:253], v[46:47] op_sel_hi:[1,0,1]
	v_cvt_pk_f32_fp8_e32 v[224:225], v148
	v_cvt_pk_f32_fp8_sdwa v[226:227], v148 src0_sel:WORD_1
	v_cvt_pk_f32_fp8_e32 v[228:229], v149
	v_cvt_pk_f32_fp8_sdwa v[230:231], v149 src0_sel:WORD_1
	v_pk_fma_f32 v[32:33], v[224:225], v[252:253], v[32:33] op_sel:[0,1,0] op_sel_hi:[1,1,1]
	v_pk_fma_f32 v[34:35], v[226:227], v[252:253], v[34:35] op_sel:[0,1,0] op_sel_hi:[1,1,1]
	v_pk_fma_f32 v[36:37], v[228:229], v[252:253], v[36:37] op_sel:[0,1,0] op_sel_hi:[1,1,1]
	v_pk_fma_f32 v[38:39], v[230:231], v[252:253], v[38:39] op_sel:[0,1,0] op_sel_hi:[1,1,1]
	v_cvt_pk_f32_fp8_e32 v[224:225], v150
	v_cvt_pk_f32_fp8_sdwa v[226:227], v150 src0_sel:WORD_1
	v_cvt_pk_f32_fp8_e32 v[228:229], v151
	v_cvt_pk_f32_fp8_sdwa v[230:231], v151 src0_sel:WORD_1
	v_pk_fma_f32 v[40:41], v[224:225], v[252:253], v[40:41] op_sel:[0,1,0] op_sel_hi:[1,1,1]
	v_pk_fma_f32 v[42:43], v[226:227], v[252:253], v[42:43] op_sel:[0,1,0] op_sel_hi:[1,1,1]
	v_pk_fma_f32 v[44:45], v[228:229], v[252:253], v[44:45] op_sel:[0,1,0] op_sel_hi:[1,1,1]
	v_pk_fma_f32 v[46:47], v[230:231], v[252:253], v[46:47] op_sel:[0,1,0] op_sel_hi:[1,1,1]
	v_cvt_pk_f32_fp8_e32 v[224:225], v152
	v_cvt_pk_f32_fp8_sdwa v[226:227], v152 src0_sel:WORD_1
	v_cvt_pk_f32_fp8_e32 v[228:229], v153
	v_cvt_pk_f32_fp8_sdwa v[230:231], v153 src0_sel:WORD_1
	v_pk_fma_f32 v[32:33], v[224:225], v[254:255], v[32:33] op_sel_hi:[1,0,1]
	v_pk_fma_f32 v[34:35], v[226:227], v[254:255], v[34:35] op_sel_hi:[1,0,1]
	v_pk_fma_f32 v[36:37], v[228:229], v[254:255], v[36:37] op_sel_hi:[1,0,1]
	v_pk_fma_f32 v[38:39], v[230:231], v[254:255], v[38:39] op_sel_hi:[1,0,1]
	v_cvt_pk_f32_fp8_e32 v[224:225], v154
	v_cvt_pk_f32_fp8_sdwa v[226:227], v154 src0_sel:WORD_1
	v_cvt_pk_f32_fp8_e32 v[228:229], v155
	v_cvt_pk_f32_fp8_sdwa v[230:231], v155 src0_sel:WORD_1
	v_pk_fma_f32 v[40:41], v[224:225], v[254:255], v[40:41] op_sel_hi:[1,0,1]
	v_pk_fma_f32 v[42:43], v[226:227], v[254:255], v[42:43] op_sel_hi:[1,0,1]
	v_pk_fma_f32 v[44:45], v[228:229], v[254:255], v[44:45] op_sel_hi:[1,0,1]
	v_pk_fma_f32 v[46:47], v[230:231], v[254:255], v[46:47] op_sel_hi:[1,0,1]
	v_cvt_pk_f32_fp8_e32 v[224:225], v156
	v_cvt_pk_f32_fp8_sdwa v[226:227], v156 src0_sel:WORD_1
	v_cvt_pk_f32_fp8_e32 v[228:229], v157
	v_cvt_pk_f32_fp8_sdwa v[230:231], v157 src0_sel:WORD_1
	v_pk_fma_f32 v[32:33], v[224:225], v[254:255], v[32:33] op_sel:[0,1,0] op_sel_hi:[1,1,1]
	v_pk_fma_f32 v[34:35], v[226:227], v[254:255], v[34:35] op_sel:[0,1,0] op_sel_hi:[1,1,1]
	v_pk_fma_f32 v[36:37], v[228:229], v[254:255], v[36:37] op_sel:[0,1,0] op_sel_hi:[1,1,1]
	v_pk_fma_f32 v[38:39], v[230:231], v[254:255], v[38:39] op_sel:[0,1,0] op_sel_hi:[1,1,1]
	v_cvt_pk_f32_fp8_e32 v[224:225], v158
	v_cvt_pk_f32_fp8_sdwa v[226:227], v158 src0_sel:WORD_1
	v_cvt_pk_f32_fp8_e32 v[228:229], v159
	v_cvt_pk_f32_fp8_sdwa v[230:231], v159 src0_sel:WORD_1
	v_pk_fma_f32 v[40:41], v[224:225], v[254:255], v[40:41] op_sel:[0,1,0] op_sel_hi:[1,1,1]
	v_pk_fma_f32 v[42:43], v[226:227], v[254:255], v[42:43] op_sel:[0,1,0] op_sel_hi:[1,1,1]
	v_pk_fma_f32 v[44:45], v[228:229], v[254:255], v[44:45] op_sel:[0,1,0] op_sel_hi:[1,1,1]
	v_pk_fma_f32 v[46:47], v[230:231], v[254:255], v[46:47] op_sel:[0,1,0] op_sel_hi:[1,1,1]
	s_sub_i32 s90, s90, 1
	s_cmp_eq_u32 s90, 0
	s_cbranch_scc1 .LV_sw2

.LV_t3_s1:
	s_cmp_eq_u32 s21, 255
	s_cbranch_scc1 .LV_done
	s_waitcnt lgkmcnt(0)
	buffer_load_dwordx4 v[128:131], v[232:233], s[60:63], 0 idxen offen
	buffer_load_dwordx4 v[132:135], v[234:235], s[60:63], 0 idxen offen
	buffer_load_dwordx4 v[136:139], v[236:237], s[60:63], 0 idxen offen
	buffer_load_dwordx4 v[140:143], v[238:239], s[60:63], 0 idxen offen
	ds_read_b32 v232, v213 offset:96
	ds_read_b32 v234, v213 offset:100
	ds_read_b32 v236, v213 offset:104
	ds_read_b32 v238, v213 offset:108
	ds_read_b128 v[248:251], v213 offset:5024
	s_waitcnt vmcnt(16)
	v_cvt_pk_f32_fp8_e32 v[224:225], v144
	v_cvt_pk_f32_fp8_sdwa v[226:227], v144 src0_sel:WORD_1
	v_cvt_pk_f32_fp8_e32 v[228:229], v145
	v_cvt_pk_f32_fp8_sdwa v[230:231], v145 src0_sel:WORD_1
	v_pk_fma_f32 v[48:49], v[224:225], v[252:253], v[48:49] op_sel_hi:[1,0,1]
	v_pk_fma_f32 v[50:51], v[226:227], v[252:253], v[50:51] op_sel_hi:[1,0,1]
	v_pk_fma_f32 v[52:53], v[228:229], v[252:253], v[52:53] op_sel_hi:[1,0,1]
	v_pk_fma_f32 v[54:55], v[230:231], v[252:253], v[54:55] op_sel_hi:[1,0,1]
	v_cvt_pk_f32_fp8_e32 v[224:225], v146
	v_cvt_pk_f32_fp8_sdwa v[226:227], v146 src0_sel:WORD_1
	v_cvt_pk_f32_fp8_e32 v[228:229], v147
	v_cvt_pk_f32_fp8_sdwa v[230:231], v147 src0_sel:WORD_1
	v_pk_fma_f32 v[56:57], v[224:225], v[252:253], v[56:57] op_sel_hi:[1,0,1]
	v_pk_fma_f32 v[58:59], v[226:227], v[252:253], v[58:59] op_sel_hi:[1,0,1]
	v_pk_fma_f32 v[60:61], v[228:229], v[252:253], v[60:61] op_sel_hi:[1,0,1]
	v_pk_fma_f32 v[62:63], v[230:231], v[252:253], v[62:63] op_sel_hi:[1,0,1]
	v_cvt_pk_f32_fp8_e32 v[224:225], v148
	v_cvt_pk_f32_fp8_sdwa v[226:227], v148 src0_sel:WORD_1
	v_cvt_pk_f32_fp8_e32 v[228:229], v149
	v_cvt_pk_f32_fp8_sdwa v[230:231], v149 src0_sel:WORD_1
	v_pk_fma_f32 v[48:49], v[224:225], v[252:253], v[48:49] op_sel:[0,1,0] op_sel_hi:[1,1,1]
	v_pk_fma_f32 v[50:51], v[226:227], v[252:253], v[50:51] op_sel:[0,1,0] op_sel_hi:[1,1,1]
	v_pk_fma_f32 v[52:53], v[228:229], v[252:253], v[52:53] op_sel:[0,1,0] op_sel_hi:[1,1,1]
	v_pk_fma_f32 v[54:55], v[230:231], v[252:253], v[54:55] op_sel:[0,1,0] op_sel_hi:[1,1,1]
	v_cvt_pk_f32_fp8_e32 v[224:225], v150
	v_cvt_pk_f32_fp8_sdwa v[226:227], v150 src0_sel:WORD_1
	v_cvt_pk_f32_fp8_e32 v[228:229], v151
	v_cvt_pk_f32_fp8_sdwa v[230:231], v151 src0_sel:WORD_1
	v_pk_fma_f32 v[56:57], v[224:225], v[252:253], v[56:57] op_sel:[0,1,0] op_sel_hi:[1,1,1]
	v_pk_fma_f32 v[58:59], v[226:227], v[252:253], v[58:59] op_sel:[0,1,0] op_sel_hi:[1,1,1]
	v_pk_fma_f32 v[60:61], v[228:229], v[252:253], v[60:61] op_sel:[0,1,0] op_sel_hi:[1,1,1]
	v_pk_fma_f32 v[62:63], v[230:231], v[252:253], v[62:63] op_sel:[0,1,0] op_sel_hi:[1,1,1]
	v_cvt_pk_f32_fp8_e32 v[224:225], v152
	v_cvt_pk_f32_fp8_sdwa v[226:227], v152 src0_sel:WORD_1
	v_cvt_pk_f32_fp8_e32 v[228:229], v153
	v_cvt_pk_f32_fp8_sdwa v[230:231], v153 src0_sel:WORD_1
	v_pk_fma_f32 v[48:49], v[224:225], v[254:255], v[48:49] op_sel_hi:[1,0,1]
	v_pk_fma_f32 v[50:51], v[226:227], v[254:255], v[50:51] op_sel_hi:[1,0,1]
	v_pk_fma_f32 v[52:53], v[228:229], v[254:255], v[52:53] op_sel_hi:[1,0,1]
	v_pk_fma_f32 v[54:55], v[230:231], v[254:255], v[54:55] op_sel_hi:[1,0,1]
	v_cvt_pk_f32_fp8_e32 v[224:225], v154
	v_cvt_pk_f32_fp8_sdwa v[226:227], v154 src0_sel:WORD_1
	v_cvt_pk_f32_fp8_e32 v[228:229], v155
	v_cvt_pk_f32_fp8_sdwa v[230:231], v155 src0_sel:WORD_1
	v_pk_fma_f32 v[56:57], v[224:225], v[254:255], v[56:57] op_sel_hi:[1,0,1]
	v_pk_fma_f32 v[58:59], v[226:227], v[254:255], v[58:59] op_sel_hi:[1,0,1]
	v_pk_fma_f32 v[60:61], v[228:229], v[254:255], v[60:61] op_sel_hi:[1,0,1]
	v_pk_fma_f32 v[62:63], v[230:231], v[254:255], v[62:63] op_sel_hi:[1,0,1]
	v_cvt_pk_f32_fp8_e32 v[224:225], v156
	v_cvt_pk_f32_fp8_sdwa v[226:227], v156 src0_sel:WORD_1
	v_cvt_pk_f32_fp8_e32 v[228:229], v157
	v_cvt_pk_f32_fp8_sdwa v[230:231], v157 src0_sel:WORD_1
	v_pk_fma_f32 v[48:49], v[224:225], v[254:255], v[48:49] op_sel:[0,1,0] op_sel_hi:[1,1,1]
	v_pk_fma_f32 v[50:51], v[226:227], v[254:255], v[50:51] op_sel:[0,1,0] op_sel_hi:[1,1,1]
	v_pk_fma_f32 v[52:53], v[228:229], v[254:255], v[52:53] op_sel:[0,1,0] op_sel_hi:[1,1,1]
	v_pk_fma_f32 v[54:55], v[230:231], v[254:255], v[54:55] op_sel:[0,1,0] op_sel_hi:[1,1,1]
	v_cvt_pk_f32_fp8_e32 v[224:225], v158
	v_cvt_pk_f32_fp8_sdwa v[226:227], v158 src0_sel:WORD_1
	v_cvt_pk_f32_fp8_e32 v[228:229], v159
	v_cvt_pk_f32_fp8_sdwa v[230:231], v159 src0_sel:WORD_1
	v_pk_fma_f32 v[56:57], v[224:225], v[254:255], v[56:57] op_sel:[0,1,0] op_sel_hi:[1,1,1]
	v_pk_fma_f32 v[58:59], v[226:227], v[254:255], v[58:59] op_sel:[0,1,0] op_sel_hi:[1,1,1]
	v_pk_fma_f32 v[60:61], v[228:229], v[254:255], v[60:61] op_sel:[0,1,0] op_sel_hi:[1,1,1]
	v_pk_fma_f32 v[62:63], v[230:231], v[254:255], v[62:63] op_sel:[0,1,0] op_sel_hi:[1,1,1]
	s_sub_i32 s90, s90, 1
	s_cmp_eq_u32 s90, 0
	s_cbranch_scc1 .LV_sw2

.LV_t4_s1:
	s_cmp_eq_u32 s21, 255
	s_cbranch_scc1 .LV_done
	s_waitcnt lgkmcnt(0)
	buffer_load_dwordx4 v[128:131], v[232:233], s[60:63], 0 idxen offen
	buffer_load_dwordx4 v[132:135], v[234:235], s[60:63], 0 idxen offen
	buffer_load_dwordx4 v[136:139], v[236:237], s[60:63], 0 idxen offen
	buffer_load_dwordx4 v[140:143], v[238:239], s[60:63], 0 idxen offen
	ds_read_b32 v232, v213 offset:96
	ds_read_b32 v234, v213 offset:100
	ds_read_b32 v236, v213 offset:104
	ds_read_b32 v238, v213 offset:108
	ds_read_b128 v[248:251], v213 offset:5024
	s_waitcnt vmcnt(16)
	v_cvt_pk_f32_fp8_e32 v[224:225], v144
	v_cvt_pk_f32_fp8_sdwa v[226:227], v144 src0_sel:WORD_1
	v_cvt_pk_f32_fp8_e32 v[228:229], v145
	v_cvt_pk_f32_fp8_sdwa v[230:231], v145 src0_sel:WORD_1
	v_pk_fma_f32 v[64:65], v[224:225], v[252:253], v[64:65] op_sel_hi:[1,0,1]
	v_pk_fma_f32 v[66:67], v[226:227], v[252:253], v[66:67] op_sel_hi:[1,0,1]
	v_pk_fma_f32 v[68:69], v[228:229], v[252:253], v[68:69] op_sel_hi:[1,0,1]
	v_pk_fma_f32 v[70:71], v[230:231], v[252:253], v[70:71] op_sel_hi:[1,0,1]
	v_cvt_pk_f32_fp8_e32 v[224:225], v146
	v_cvt_pk_f32_fp8_sdwa v[226:227], v146 src0_sel:WORD_1
	v_cvt_pk_f32_fp8_e32 v[228:229], v147
	v_cvt_pk_f32_fp8_sdwa v[230:231], v147 src0_sel:WORD_1
	v_pk_fma_f32 v[72:73], v[224:225], v[252:253], v[72:73] op_sel_hi:[1,0,1]
	v_pk_fma_f32 v[74:75], v[226:227], v[252:253], v[74:75] op_sel_hi:[1,0,1]
	v_pk_fma_f32 v[76:77], v[228:229], v[252:253], v[76:77] op_sel_hi:[1,0,1]
	v_pk_fma_f32 v[78:79], v[230:231], v[252:253], v[78:79] op_sel_hi:[1,0,1]
	v_cvt_pk_f32_fp8_e32 v[224:225], v148
	v_cvt_pk_f32_fp8_sdwa v[226:227], v148 src0_sel:WORD_1
	v_cvt_pk_f32_fp8_e32 v[228:229], v149
	v_cvt_pk_f32_fp8_sdwa v[230:231], v149 src0_sel:WORD_1
	v_pk_fma_f32 v[64:65], v[224:225], v[252:253], v[64:65] op_sel:[0,1,0] op_sel_hi:[1,1,1]
	v_pk_fma_f32 v[66:67], v[226:227], v[252:253], v[66:67] op_sel:[0,1,0] op_sel_hi:[1,1,1]
	v_pk_fma_f32 v[68:69], v[228:229], v[252:253], v[68:69] op_sel:[0,1,0] op_sel_hi:[1,1,1]
	v_pk_fma_f32 v[70:71], v[230:231], v[252:253], v[70:71] op_sel:[0,1,0] op_sel_hi:[1,1,1]
	v_cvt_pk_f32_fp8_e32 v[224:225], v150
	v_cvt_pk_f32_fp8_sdwa v[226:227], v150 src0_sel:WORD_1
	v_cvt_pk_f32_fp8_e32 v[228:229], v151
	v_cvt_pk_f32_fp8_sdwa v[230:231], v151 src0_sel:WORD_1
	v_pk_fma_f32 v[72:73], v[224:225], v[252:253], v[72:73] op_sel:[0,1,0] op_sel_hi:[1,1,1]
	v_pk_fma_f32 v[74:75], v[226:227], v[252:253], v[74:75] op_sel:[0,1,0] op_sel_hi:[1,1,1]
	v_pk_fma_f32 v[76:77], v[228:229], v[252:253], v[76:77] op_sel:[0,1,0] op_sel_hi:[1,1,1]
	v_pk_fma_f32 v[78:79], v[230:231], v[252:253], v[78:79] op_sel:[0,1,0] op_sel_hi:[1,1,1]
	v_cvt_pk_f32_fp8_e32 v[224:225], v152
	v_cvt_pk_f32_fp8_sdwa v[226:227], v152 src0_sel:WORD_1
	v_cvt_pk_f32_fp8_e32 v[228:229], v153
	v_cvt_pk_f32_fp8_sdwa v[230:231], v153 src0_sel:WORD_1
	v_pk_fma_f32 v[64:65], v[224:225], v[254:255], v[64:65] op_sel_hi:[1,0,1]
	v_pk_fma_f32 v[66:67], v[226:227], v[254:255], v[66:67] op_sel_hi:[1,0,1]
	v_pk_fma_f32 v[68:69], v[228:229], v[254:255], v[68:69] op_sel_hi:[1,0,1]
	v_pk_fma_f32 v[70:71], v[230:231], v[254:255], v[70:71] op_sel_hi:[1,0,1]
	v_cvt_pk_f32_fp8_e32 v[224:225], v154
	v_cvt_pk_f32_fp8_sdwa v[226:227], v154 src0_sel:WORD_1
	v_cvt_pk_f32_fp8_e32 v[228:229], v155
	v_cvt_pk_f32_fp8_sdwa v[230:231], v155 src0_sel:WORD_1
	v_pk_fma_f32 v[72:73], v[224:225], v[254:255], v[72:73] op_sel_hi:[1,0,1]
	v_pk_fma_f32 v[74:75], v[226:227], v[254:255], v[74:75] op_sel_hi:[1,0,1]
	v_pk_fma_f32 v[76:77], v[228:229], v[254:255], v[76:77] op_sel_hi:[1,0,1]
	v_pk_fma_f32 v[78:79], v[230:231], v[254:255], v[78:79] op_sel_hi:[1,0,1]
	v_cvt_pk_f32_fp8_e32 v[224:225], v156
	v_cvt_pk_f32_fp8_sdwa v[226:227], v156 src0_sel:WORD_1
	v_cvt_pk_f32_fp8_e32 v[228:229], v157
	v_cvt_pk_f32_fp8_sdwa v[230:231], v157 src0_sel:WORD_1
	v_pk_fma_f32 v[64:65], v[224:225], v[254:255], v[64:65] op_sel:[0,1,0] op_sel_hi:[1,1,1]
	v_pk_fma_f32 v[66:67], v[226:227], v[254:255], v[66:67] op_sel:[0,1,0] op_sel_hi:[1,1,1]
	v_pk_fma_f32 v[68:69], v[228:229], v[254:255], v[68:69] op_sel:[0,1,0] op_sel_hi:[1,1,1]
	v_pk_fma_f32 v[70:71], v[230:231], v[254:255], v[70:71] op_sel:[0,1,0] op_sel_hi:[1,1,1]
	v_cvt_pk_f32_fp8_e32 v[224:225], v158
	v_cvt_pk_f32_fp8_sdwa v[226:227], v158 src0_sel:WORD_1
	v_cvt_pk_f32_fp8_e32 v[228:229], v159
	v_cvt_pk_f32_fp8_sdwa v[230:231], v159 src0_sel:WORD_1
	v_pk_fma_f32 v[72:73], v[224:225], v[254:255], v[72:73] op_sel:[0,1,0] op_sel_hi:[1,1,1]
	v_pk_fma_f32 v[74:75], v[226:227], v[254:255], v[74:75] op_sel:[0,1,0] op_sel_hi:[1,1,1]
	v_pk_fma_f32 v[76:77], v[228:229], v[254:255], v[76:77] op_sel:[0,1,0] op_sel_hi:[1,1,1]
	v_pk_fma_f32 v[78:79], v[230:231], v[254:255], v[78:79] op_sel:[0,1,0] op_sel_hi:[1,1,1]
	s_sub_i32 s90, s90, 1
	s_cmp_eq_u32 s90, 0
	s_cbranch_scc1 .LV_sw2

.LV_t5_s1:
	s_cmp_eq_u32 s21, 255
	s_cbranch_scc1 .LV_done
	s_waitcnt lgkmcnt(0)
	buffer_load_dwordx4 v[128:131], v[232:233], s[60:63], 0 idxen offen
	buffer_load_dwordx4 v[132:135], v[234:235], s[60:63], 0 idxen offen
	buffer_load_dwordx4 v[136:139], v[236:237], s[60:63], 0 idxen offen
	buffer_load_dwordx4 v[140:143], v[238:239], s[60:63], 0 idxen offen
	ds_read_b32 v232, v213 offset:96
	ds_read_b32 v234, v213 offset:100
	ds_read_b32 v236, v213 offset:104
	ds_read_b32 v238, v213 offset:108
	ds_read_b128 v[248:251], v213 offset:5024
	s_waitcnt vmcnt(16)
	v_cvt_pk_f32_fp8_e32 v[224:225], v144
	v_cvt_pk_f32_fp8_sdwa v[226:227], v144 src0_sel:WORD_1
	v_cvt_pk_f32_fp8_e32 v[228:229], v145
	v_cvt_pk_f32_fp8_sdwa v[230:231], v145 src0_sel:WORD_1
	v_pk_fma_f32 v[80:81], v[224:225], v[252:253], v[80:81] op_sel_hi:[1,0,1]
	v_pk_fma_f32 v[82:83], v[226:227], v[252:253], v[82:83] op_sel_hi:[1,0,1]
	v_pk_fma_f32 v[84:85], v[228:229], v[252:253], v[84:85] op_sel_hi:[1,0,1]
	v_pk_fma_f32 v[86:87], v[230:231], v[252:253], v[86:87] op_sel_hi:[1,0,1]
	v_cvt_pk_f32_fp8_e32 v[224:225], v146
	v_cvt_pk_f32_fp8_sdwa v[226:227], v146 src0_sel:WORD_1
	v_cvt_pk_f32_fp8_e32 v[228:229], v147
	v_cvt_pk_f32_fp8_sdwa v[230:231], v147 src0_sel:WORD_1
	v_pk_fma_f32 v[88:89], v[224:225], v[252:253], v[88:89] op_sel_hi:[1,0,1]
	v_pk_fma_f32 v[90:91], v[226:227], v[252:253], v[90:91] op_sel_hi:[1,0,1]
	v_pk_fma_f32 v[92:93], v[228:229], v[252:253], v[92:93] op_sel_hi:[1,0,1]
	v_pk_fma_f32 v[94:95], v[230:231], v[252:253], v[94:95] op_sel_hi:[1,0,1]
	v_cvt_pk_f32_fp8_e32 v[224:225], v148
	v_cvt_pk_f32_fp8_sdwa v[226:227], v148 src0_sel:WORD_1
	v_cvt_pk_f32_fp8_e32 v[228:229], v149
	v_cvt_pk_f32_fp8_sdwa v[230:231], v149 src0_sel:WORD_1
	v_pk_fma_f32 v[80:81], v[224:225], v[252:253], v[80:81] op_sel:[0,1,0] op_sel_hi:[1,1,1]
	v_pk_fma_f32 v[82:83], v[226:227], v[252:253], v[82:83] op_sel:[0,1,0] op_sel_hi:[1,1,1]
	v_pk_fma_f32 v[84:85], v[228:229], v[252:253], v[84:85] op_sel:[0,1,0] op_sel_hi:[1,1,1]
	v_pk_fma_f32 v[86:87], v[230:231], v[252:253], v[86:87] op_sel:[0,1,0] op_sel_hi:[1,1,1]
	v_cvt_pk_f32_fp8_e32 v[224:225], v150
	v_cvt_pk_f32_fp8_sdwa v[226:227], v150 src0_sel:WORD_1
	v_cvt_pk_f32_fp8_e32 v[228:229], v151
	v_cvt_pk_f32_fp8_sdwa v[230:231], v151 src0_sel:WORD_1
	v_pk_fma_f32 v[88:89], v[224:225], v[252:253], v[88:89] op_sel:[0,1,0] op_sel_hi:[1,1,1]
	v_pk_fma_f32 v[90:91], v[226:227], v[252:253], v[90:91] op_sel:[0,1,0] op_sel_hi:[1,1,1]
	v_pk_fma_f32 v[92:93], v[228:229], v[252:253], v[92:93] op_sel:[0,1,0] op_sel_hi:[1,1,1]
	v_pk_fma_f32 v[94:95], v[230:231], v[252:253], v[94:95] op_sel:[0,1,0] op_sel_hi:[1,1,1]
	v_cvt_pk_f32_fp8_e32 v[224:225], v152
	v_cvt_pk_f32_fp8_sdwa v[226:227], v152 src0_sel:WORD_1
	v_cvt_pk_f32_fp8_e32 v[228:229], v153
	v_cvt_pk_f32_fp8_sdwa v[230:231], v153 src0_sel:WORD_1
	v_pk_fma_f32 v[80:81], v[224:225], v[254:255], v[80:81] op_sel_hi:[1,0,1]
	v_pk_fma_f32 v[82:83], v[226:227], v[254:255], v[82:83] op_sel_hi:[1,0,1]
	v_pk_fma_f32 v[84:85], v[228:229], v[254:255], v[84:85] op_sel_hi:[1,0,1]
	v_pk_fma_f32 v[86:87], v[230:231], v[254:255], v[86:87] op_sel_hi:[1,0,1]
	v_cvt_pk_f32_fp8_e32 v[224:225], v154
	v_cvt_pk_f32_fp8_sdwa v[226:227], v154 src0_sel:WORD_1
	v_cvt_pk_f32_fp8_e32 v[228:229], v155
	v_cvt_pk_f32_fp8_sdwa v[230:231], v155 src0_sel:WORD_1
	v_pk_fma_f32 v[88:89], v[224:225], v[254:255], v[88:89] op_sel_hi:[1,0,1]
	v_pk_fma_f32 v[90:91], v[226:227], v[254:255], v[90:91] op_sel_hi:[1,0,1]
	v_pk_fma_f32 v[92:93], v[228:229], v[254:255], v[92:93] op_sel_hi:[1,0,1]
	v_pk_fma_f32 v[94:95], v[230:231], v[254:255], v[94:95] op_sel_hi:[1,0,1]
	v_cvt_pk_f32_fp8_e32 v[224:225], v156
	v_cvt_pk_f32_fp8_sdwa v[226:227], v156 src0_sel:WORD_1
	v_cvt_pk_f32_fp8_e32 v[228:229], v157
	v_cvt_pk_f32_fp8_sdwa v[230:231], v157 src0_sel:WORD_1
	v_pk_fma_f32 v[80:81], v[224:225], v[254:255], v[80:81] op_sel:[0,1,0] op_sel_hi:[1,1,1]
	v_pk_fma_f32 v[82:83], v[226:227], v[254:255], v[82:83] op_sel:[0,1,0] op_sel_hi:[1,1,1]
	v_pk_fma_f32 v[84:85], v[228:229], v[254:255], v[84:85] op_sel:[0,1,0] op_sel_hi:[1,1,1]
	v_pk_fma_f32 v[86:87], v[230:231], v[254:255], v[86:87] op_sel:[0,1,0] op_sel_hi:[1,1,1]
	v_cvt_pk_f32_fp8_e32 v[224:225], v158
	v_cvt_pk_f32_fp8_sdwa v[226:227], v158 src0_sel:WORD_1
	v_cvt_pk_f32_fp8_e32 v[228:229], v159
	v_cvt_pk_f32_fp8_sdwa v[230:231], v159 src0_sel:WORD_1
	v_pk_fma_f32 v[88:89], v[224:225], v[254:255], v[88:89] op_sel:[0,1,0] op_sel_hi:[1,1,1]
	v_pk_fma_f32 v[90:91], v[226:227], v[254:255], v[90:91] op_sel:[0,1,0] op_sel_hi:[1,1,1]
	v_pk_fma_f32 v[92:93], v[228:229], v[254:255], v[92:93] op_sel:[0,1,0] op_sel_hi:[1,1,1]
	v_pk_fma_f32 v[94:95], v[230:231], v[254:255], v[94:95] op_sel:[0,1,0] op_sel_hi:[1,1,1]
	s_sub_i32 s90, s90, 1
	s_cmp_eq_u32 s90, 0
	s_cbranch_scc1 .LV_sw2

.LV_t6_s1:
	s_cmp_eq_u32 s21, 255
	s_cbranch_scc1 .LV_done
	s_waitcnt lgkmcnt(0)
	buffer_load_dwordx4 v[128:131], v[232:233], s[60:63], 0 idxen offen
	buffer_load_dwordx4 v[132:135], v[234:235], s[60:63], 0 idxen offen
	buffer_load_dwordx4 v[136:139], v[236:237], s[60:63], 0 idxen offen
	buffer_load_dwordx4 v[140:143], v[238:239], s[60:63], 0 idxen offen
	ds_read_b32 v232, v213 offset:96
	ds_read_b32 v234, v213 offset:100
	ds_read_b32 v236, v213 offset:104
	ds_read_b32 v238, v213 offset:108
	ds_read_b128 v[248:251], v213 offset:5024
	s_waitcnt vmcnt(16)
	v_cvt_pk_f32_fp8_e32 v[224:225], v144
	v_cvt_pk_f32_fp8_sdwa v[226:227], v144 src0_sel:WORD_1
	v_cvt_pk_f32_fp8_e32 v[228:229], v145
	v_cvt_pk_f32_fp8_sdwa v[230:231], v145 src0_sel:WORD_1
	v_pk_fma_f32 v[96:97], v[224:225], v[252:253], v[96:97] op_sel_hi:[1,0,1]
	v_pk_fma_f32 v[98:99], v[226:227], v[252:253], v[98:99] op_sel_hi:[1,0,1]
	v_pk_fma_f32 v[100:101], v[228:229], v[252:253], v[100:101] op_sel_hi:[1,0,1]
	v_pk_fma_f32 v[102:103], v[230:231], v[252:253], v[102:103] op_sel_hi:[1,0,1]
	v_cvt_pk_f32_fp8_e32 v[224:225], v146
	v_cvt_pk_f32_fp8_sdwa v[226:227], v146 src0_sel:WORD_1
	v_cvt_pk_f32_fp8_e32 v[228:229], v147
	v_cvt_pk_f32_fp8_sdwa v[230:231], v147 src0_sel:WORD_1
	v_pk_fma_f32 v[104:105], v[224:225], v[252:253], v[104:105] op_sel_hi:[1,0,1]
	v_pk_fma_f32 v[106:107], v[226:227], v[252:253], v[106:107] op_sel_hi:[1,0,1]
	v_pk_fma_f32 v[108:109], v[228:229], v[252:253], v[108:109] op_sel_hi:[1,0,1]
	v_pk_fma_f32 v[110:111], v[230:231], v[252:253], v[110:111] op_sel_hi:[1,0,1]
	v_cvt_pk_f32_fp8_e32 v[224:225], v148
	v_cvt_pk_f32_fp8_sdwa v[226:227], v148 src0_sel:WORD_1
	v_cvt_pk_f32_fp8_e32 v[228:229], v149
	v_cvt_pk_f32_fp8_sdwa v[230:231], v149 src0_sel:WORD_1
	v_pk_fma_f32 v[96:97], v[224:225], v[252:253], v[96:97] op_sel:[0,1,0] op_sel_hi:[1,1,1]
	v_pk_fma_f32 v[98:99], v[226:227], v[252:253], v[98:99] op_sel:[0,1,0] op_sel_hi:[1,1,1]
	v_pk_fma_f32 v[100:101], v[228:229], v[252:253], v[100:101] op_sel:[0,1,0] op_sel_hi:[1,1,1]
	v_pk_fma_f32 v[102:103], v[230:231], v[252:253], v[102:103] op_sel:[0,1,0] op_sel_hi:[1,1,1]
	v_cvt_pk_f32_fp8_e32 v[224:225], v150
	v_cvt_pk_f32_fp8_sdwa v[226:227], v150 src0_sel:WORD_1
	v_cvt_pk_f32_fp8_e32 v[228:229], v151
	v_cvt_pk_f32_fp8_sdwa v[230:231], v151 src0_sel:WORD_1
	v_pk_fma_f32 v[104:105], v[224:225], v[252:253], v[104:105] op_sel:[0,1,0] op_sel_hi:[1,1,1]
	v_pk_fma_f32 v[106:107], v[226:227], v[252:253], v[106:107] op_sel:[0,1,0] op_sel_hi:[1,1,1]
	v_pk_fma_f32 v[108:109], v[228:229], v[252:253], v[108:109] op_sel:[0,1,0] op_sel_hi:[1,1,1]
	v_pk_fma_f32 v[110:111], v[230:231], v[252:253], v[110:111] op_sel:[0,1,0] op_sel_hi:[1,1,1]
	v_cvt_pk_f32_fp8_e32 v[224:225], v152
	v_cvt_pk_f32_fp8_sdwa v[226:227], v152 src0_sel:WORD_1
	v_cvt_pk_f32_fp8_e32 v[228:229], v153
	v_cvt_pk_f32_fp8_sdwa v[230:231], v153 src0_sel:WORD_1
	v_pk_fma_f32 v[96:97], v[224:225], v[254:255], v[96:97] op_sel_hi:[1,0,1]
	v_pk_fma_f32 v[98:99], v[226:227], v[254:255], v[98:99] op_sel_hi:[1,0,1]
	v_pk_fma_f32 v[100:101], v[228:229], v[254:255], v[100:101] op_sel_hi:[1,0,1]
	v_pk_fma_f32 v[102:103], v[230:231], v[254:255], v[102:103] op_sel_hi:[1,0,1]
	v_cvt_pk_f32_fp8_e32 v[224:225], v154
	v_cvt_pk_f32_fp8_sdwa v[226:227], v154 src0_sel:WORD_1
	v_cvt_pk_f32_fp8_e32 v[228:229], v155
	v_cvt_pk_f32_fp8_sdwa v[230:231], v155 src0_sel:WORD_1
	v_pk_fma_f32 v[104:105], v[224:225], v[254:255], v[104:105] op_sel_hi:[1,0,1]
	v_pk_fma_f32 v[106:107], v[226:227], v[254:255], v[106:107] op_sel_hi:[1,0,1]
	v_pk_fma_f32 v[108:109], v[228:229], v[254:255], v[108:109] op_sel_hi:[1,0,1]
	v_pk_fma_f32 v[110:111], v[230:231], v[254:255], v[110:111] op_sel_hi:[1,0,1]
	v_cvt_pk_f32_fp8_e32 v[224:225], v156
	v_cvt_pk_f32_fp8_sdwa v[226:227], v156 src0_sel:WORD_1
	v_cvt_pk_f32_fp8_e32 v[228:229], v157
	v_cvt_pk_f32_fp8_sdwa v[230:231], v157 src0_sel:WORD_1
	v_pk_fma_f32 v[96:97], v[224:225], v[254:255], v[96:97] op_sel:[0,1,0] op_sel_hi:[1,1,1]
	v_pk_fma_f32 v[98:99], v[226:227], v[254:255], v[98:99] op_sel:[0,1,0] op_sel_hi:[1,1,1]
	v_pk_fma_f32 v[100:101], v[228:229], v[254:255], v[100:101] op_sel:[0,1,0] op_sel_hi:[1,1,1]
	v_pk_fma_f32 v[102:103], v[230:231], v[254:255], v[102:103] op_sel:[0,1,0] op_sel_hi:[1,1,1]
	v_cvt_pk_f32_fp8_e32 v[224:225], v158
	v_cvt_pk_f32_fp8_sdwa v[226:227], v158 src0_sel:WORD_1
	v_cvt_pk_f32_fp8_e32 v[228:229], v159
	v_cvt_pk_f32_fp8_sdwa v[230:231], v159 src0_sel:WORD_1
	v_pk_fma_f32 v[104:105], v[224:225], v[254:255], v[104:105] op_sel:[0,1,0] op_sel_hi:[1,1,1]
	v_pk_fma_f32 v[106:107], v[226:227], v[254:255], v[106:107] op_sel:[0,1,0] op_sel_hi:[1,1,1]
	v_pk_fma_f32 v[108:109], v[228:229], v[254:255], v[108:109] op_sel:[0,1,0] op_sel_hi:[1,1,1]
	v_pk_fma_f32 v[110:111], v[230:231], v[254:255], v[110:111] op_sel:[0,1,0] op_sel_hi:[1,1,1]
	s_sub_i32 s90, s90, 1
	s_cmp_eq_u32 s90, 0
	s_cbranch_scc1 .LV_sw2

.LV_t7_s1:
	s_cmp_eq_u32 s21, 255
	s_cbranch_scc1 .LV_done
	s_waitcnt lgkmcnt(0)
	buffer_load_dwordx4 v[128:131], v[232:233], s[60:63], 0 idxen offen
	buffer_load_dwordx4 v[132:135], v[234:235], s[60:63], 0 idxen offen
	buffer_load_dwordx4 v[136:139], v[236:237], s[60:63], 0 idxen offen
	buffer_load_dwordx4 v[140:143], v[238:239], s[60:63], 0 idxen offen
	ds_read_b32 v232, v213 offset:96
	ds_read_b32 v234, v213 offset:100
	ds_read_b32 v236, v213 offset:104
	ds_read_b32 v238, v213 offset:108
	ds_read_b128 v[248:251], v213 offset:5024
	s_waitcnt vmcnt(16)
	v_cvt_pk_f32_fp8_e32 v[224:225], v144
	v_cvt_pk_f32_fp8_sdwa v[226:227], v144 src0_sel:WORD_1
	v_cvt_pk_f32_fp8_e32 v[228:229], v145
	v_cvt_pk_f32_fp8_sdwa v[230:231], v145 src0_sel:WORD_1
	v_pk_fma_f32 v[112:113], v[224:225], v[252:253], v[112:113] op_sel_hi:[1,0,1]
	v_pk_fma_f32 v[114:115], v[226:227], v[252:253], v[114:115] op_sel_hi:[1,0,1]
	v_pk_fma_f32 v[116:117], v[228:229], v[252:253], v[116:117] op_sel_hi:[1,0,1]
	v_pk_fma_f32 v[118:119], v[230:231], v[252:253], v[118:119] op_sel_hi:[1,0,1]
	v_cvt_pk_f32_fp8_e32 v[224:225], v146
	v_cvt_pk_f32_fp8_sdwa v[226:227], v146 src0_sel:WORD_1
	v_cvt_pk_f32_fp8_e32 v[228:229], v147
	v_cvt_pk_f32_fp8_sdwa v[230:231], v147 src0_sel:WORD_1
	v_pk_fma_f32 v[120:121], v[224:225], v[252:253], v[120:121] op_sel_hi:[1,0,1]
	v_pk_fma_f32 v[122:123], v[226:227], v[252:253], v[122:123] op_sel_hi:[1,0,1]
	v_pk_fma_f32 v[124:125], v[228:229], v[252:253], v[124:125] op_sel_hi:[1,0,1]
	v_pk_fma_f32 v[126:127], v[230:231], v[252:253], v[126:127] op_sel_hi:[1,0,1]
	v_cvt_pk_f32_fp8_e32 v[224:225], v148
	v_cvt_pk_f32_fp8_sdwa v[226:227], v148 src0_sel:WORD_1
	v_cvt_pk_f32_fp8_e32 v[228:229], v149
	v_cvt_pk_f32_fp8_sdwa v[230:231], v149 src0_sel:WORD_1
	v_pk_fma_f32 v[112:113], v[224:225], v[252:253], v[112:113] op_sel:[0,1,0] op_sel_hi:[1,1,1]
	v_pk_fma_f32 v[114:115], v[226:227], v[252:253], v[114:115] op_sel:[0,1,0] op_sel_hi:[1,1,1]
	v_pk_fma_f32 v[116:117], v[228:229], v[252:253], v[116:117] op_sel:[0,1,0] op_sel_hi:[1,1,1]
	v_pk_fma_f32 v[118:119], v[230:231], v[252:253], v[118:119] op_sel:[0,1,0] op_sel_hi:[1,1,1]
	v_cvt_pk_f32_fp8_e32 v[224:225], v150
	v_cvt_pk_f32_fp8_sdwa v[226:227], v150 src0_sel:WORD_1
	v_cvt_pk_f32_fp8_e32 v[228:229], v151
	v_cvt_pk_f32_fp8_sdwa v[230:231], v151 src0_sel:WORD_1
	v_pk_fma_f32 v[120:121], v[224:225], v[252:253], v[120:121] op_sel:[0,1,0] op_sel_hi:[1,1,1]
	v_pk_fma_f32 v[122:123], v[226:227], v[252:253], v[122:123] op_sel:[0,1,0] op_sel_hi:[1,1,1]
	v_pk_fma_f32 v[124:125], v[228:229], v[252:253], v[124:125] op_sel:[0,1,0] op_sel_hi:[1,1,1]
	v_pk_fma_f32 v[126:127], v[230:231], v[252:253], v[126:127] op_sel:[0,1,0] op_sel_hi:[1,1,1]
	v_cvt_pk_f32_fp8_e32 v[224:225], v152
	v_cvt_pk_f32_fp8_sdwa v[226:227], v152 src0_sel:WORD_1
	v_cvt_pk_f32_fp8_e32 v[228:229], v153
	v_cvt_pk_f32_fp8_sdwa v[230:231], v153 src0_sel:WORD_1
	v_pk_fma_f32 v[112:113], v[224:225], v[254:255], v[112:113] op_sel_hi:[1,0,1]
	v_pk_fma_f32 v[114:115], v[226:227], v[254:255], v[114:115] op_sel_hi:[1,0,1]
	v_pk_fma_f32 v[116:117], v[228:229], v[254:255], v[116:117] op_sel_hi:[1,0,1]
	v_pk_fma_f32 v[118:119], v[230:231], v[254:255], v[118:119] op_sel_hi:[1,0,1]
	v_cvt_pk_f32_fp8_e32 v[224:225], v154
	v_cvt_pk_f32_fp8_sdwa v[226:227], v154 src0_sel:WORD_1
	v_cvt_pk_f32_fp8_e32 v[228:229], v155
	v_cvt_pk_f32_fp8_sdwa v[230:231], v155 src0_sel:WORD_1
	v_pk_fma_f32 v[120:121], v[224:225], v[254:255], v[120:121] op_sel_hi:[1,0,1]
	v_pk_fma_f32 v[122:123], v[226:227], v[254:255], v[122:123] op_sel_hi:[1,0,1]
	v_pk_fma_f32 v[124:125], v[228:229], v[254:255], v[124:125] op_sel_hi:[1,0,1]
	v_pk_fma_f32 v[126:127], v[230:231], v[254:255], v[126:127] op_sel_hi:[1,0,1]
	v_cvt_pk_f32_fp8_e32 v[224:225], v156
	v_cvt_pk_f32_fp8_sdwa v[226:227], v156 src0_sel:WORD_1
	v_cvt_pk_f32_fp8_e32 v[228:229], v157
	v_cvt_pk_f32_fp8_sdwa v[230:231], v157 src0_sel:WORD_1
	v_pk_fma_f32 v[112:113], v[224:225], v[254:255], v[112:113] op_sel:[0,1,0] op_sel_hi:[1,1,1]
	v_pk_fma_f32 v[114:115], v[226:227], v[254:255], v[114:115] op_sel:[0,1,0] op_sel_hi:[1,1,1]
	v_pk_fma_f32 v[116:117], v[228:229], v[254:255], v[116:117] op_sel:[0,1,0] op_sel_hi:[1,1,1]
	v_pk_fma_f32 v[118:119], v[230:231], v[254:255], v[118:119] op_sel:[0,1,0] op_sel_hi:[1,1,1]
	v_cvt_pk_f32_fp8_e32 v[224:225], v158
	v_cvt_pk_f32_fp8_sdwa v[226:227], v158 src0_sel:WORD_1
	v_cvt_pk_f32_fp8_e32 v[228:229], v159
	v_cvt_pk_f32_fp8_sdwa v[230:231], v159 src0_sel:WORD_1
	v_pk_fma_f32 v[120:121], v[224:225], v[254:255], v[120:121] op_sel:[0,1,0] op_sel_hi:[1,1,1]
	v_pk_fma_f32 v[122:123], v[226:227], v[254:255], v[122:123] op_sel:[0,1,0] op_sel_hi:[1,1,1]
	v_pk_fma_f32 v[124:125], v[228:229], v[254:255], v[124:125] op_sel:[0,1,0] op_sel_hi:[1,1,1]
	v_pk_fma_f32 v[126:127], v[230:231], v[254:255], v[126:127] op_sel:[0,1,0] op_sel_hi:[1,1,1]
	s_sub_i32 s90, s90, 1
	s_cmp_eq_u32 s90, 0
	s_cbranch_scc1 .LV_sw2
